# v43 + deferred MOD reduction moved from LN1 seam to mlp1 tail on WGs>=128 (idle there)
# baseline (speedup 1.0000x reference)
; #define GAS __attribute__((address_space(1)))
; #define REP(k) _Pragma("unroll 1") for (int _r = 0; _r < (((DUPMASK >> (k)) & 1u) ? 2 : 1); ++_r)
; #define LAUNDER() do { int _t = F.tid; asm volatile("" : "+v"(_t)); F.tid = _t; F.lane = _t & 63; F.wave = __builtin_amdgcn_readfirstlane(_t >> 6); \
;         asm volatile("" : "+s"(ap)); GAS unsigned char* _w = (GAS unsigned char*)ap->ws; asm volatile("" : "+s"(_w)); F.ws = _w; ws = _w; } while (0)
; __device__ __forceinline__ void pro_b(Frame& F, CArgs a) {
;     ...
;     for (int e = F.blk * 512 + F.tid; e < DEPTH * 5 * 12288; e += F.G * 512) {
;         const int j = e % 12288, l = e / (5 * 12288);
;         float s = ((const GAS float*)a->in[I_BADA])[l * 12288 + j];
; #pragma unroll 8
;         for (int ks = 0; ks < 32; ++ks) s += modp[(size_t)ks * DEPTH * 5 * 12288 + e];
;         mod[e] = s;
;     }
; __global__ void __launch_bounds__(512, 2) mk_fwd(Args args_unused) {
;     ...
;         if (IN(p0 + 7)) REP(8) {
;             LAUNDER();
;             const bool lastl = (l == DEPTH - 1);
;             pg8::BigOrder S; S.init(ws + WS_XM, (const GAS bf16_t*)(ws + WS_W1) + (size_t)l * DFF * D, D, D, lastl ? ML : M, DFF, F.G, F.blk, lastl ? 4 : 0);
;             pg8::EpiBf16<1> E{(GAS bf16_t*)(ws + WS_H), DFF, ((const GAS float*)ap->in[I_B1]) + (size_t)l * DFF};
;             pg8::gemm_phase<pg8::EpiBf16<1>, pg8::BigOrder, false, true>(F.lds, F.tid, pg8::Gemm{D, D, D}, S, E);
;             if (!lastl && F.G == 256 && F.blk >= 128) { LAUNDER(); convert_layer(F, ap, l + 1, (F.blk - 128) * 8 + F.wave, 128 * 8, 8192, 12288); convert_layer(F, ap, l + 1, (F.blk - 128) * 8 + F.wave, 128 * 8, 15360, 16384); }
;         }
.LBB0_1655:
	s_cmpk_lt_i32 s2, 0x80
	s_cbranch_scc1 .Lmr_skip
	v_readlane_b32 s100, v255, 42
	s_nop 3
	s_cmp_gt_u32 s100, 2
	s_cbranch_scc1 .Lmr_skip
	v_writelane_b32 v200, s4, 0
	v_writelane_b32 v200, s5, 1
	v_writelane_b32 v200, s6, 2
	v_writelane_b32 v200, s7, 3
	v_writelane_b32 v200, s8, 4
	v_writelane_b32 v200, s9, 5
	v_writelane_b32 v200, s10, 6
	v_writelane_b32 v200, s11, 7
	v_writelane_b32 v200, s12, 8
	v_writelane_b32 v200, s13, 9
	v_writelane_b32 v200, s14, 10
	v_writelane_b32 v200, s15, 11
	v_writelane_b32 v200, s16, 12
	v_writelane_b32 v200, s17, 13
	v_writelane_b32 v200, s18, 14
	v_writelane_b32 v200, s19, 15
	v_writelane_b32 v200, s20, 16
	v_writelane_b32 v200, s21, 17
	v_writelane_b32 v200, s22, 18
	v_writelane_b32 v200, s23, 19
	s_add_i32 s100, s100, 1
	s_mul_i32 s100, s100, 0xf000
	s_add_i32 s101, s100, 0xf000
	s_sub_i32 s100, s100, 0x10000
	s_mov_b32 s4, s101
	v_lshl_add_u32 v2, s2, 9, v0
	v_add_u32_e32 v2, s100, v2
	s_load_dwordx2 s[14:15], s[0:1], 0x130
	v_cmp_gt_i32_e32 vcc, s4, v2
	s_waitcnt lgkmcnt(0)
	s_and_saveexec_b64 s[4:5], vcc
	s_cbranch_execz .Lmr_331
	s_load_dwordx2 s[12:13], s[0:1], 0x28
	s_lshl_b32 s8, s3, 9
	s_add_u32 s10, s14, 0x100000
	s_addc_u32 s11, s15, 0
	v_ashrrev_i32_e32 v3, 31, v2
	s_ashr_i32 s9, s8, 31
	v_lshl_add_u64 v[4:5], v[2:3], 2, s[14:15]
	s_lshl_b64 s[14:15], s[8:9], 2
	s_mov_b64 s[16:17], 0
	s_mov_b32 s9, 0x2aaaaaab
	s_movk_i32 s20, 0x3000
	s_mov_b32 s21, 0x88888889
	s_add_i32 s22, s101, -1

; #define TM_END(k) do { if ((TIMEMASK >> (k)) & 1u) tm_acc += __builtin_amdgcn_s_memrealtime() - tm_t0; } while (0)
; #define SEAM(k) do { if (IN(k) && IN((k) + 1)) GRID_BAR(); } while (0)
; #define LAUNDER() do { int _t = F.tid; asm volatile("" : "+v"(_t)); F.tid = _t; F.lane = _t & 63; F.wave = __builtin_amdgcn_readfirstlane(_t >> 6); \
;         asm volatile("" : "+s"(ap)); GAS unsigned char* _w = (GAS unsigned char*)ap->ws; asm volatile("" : "+s"(_w)); F.ws = _w; ws = _w; } while (0)
; __device__ __forceinline__ void xcd_barrier(const XcdBarrier& b) {
;     asm volatile("s_waitcnt vmcnt(0)" ::: "memory");
;     __syncthreads();
;     if (threadIdx.x == 0) {
;         unsigned* bar = b.bar;
;         __builtin_amdgcn_s_waitcnt(0);
;         unsigned nloc = b.st[0], nx = b.st[1];
;         if (nloc == 0u) { xcd_barrier_complete(bar, b.x, nloc, nx); b.st[0] = nloc; b.st[1] = nx; }
; __global__ void __launch_bounds__(512, 2) mk_fwd(Args args_unused) {
;     ...
;             if (!lastl && F.G == 256 && F.blk >= 128) { LAUNDER(); convert_layer(F, ap, l + 1, (F.blk - 128) * 8 + F.wave, 128 * 8, 8192, 12288); convert_layer(F, ap, l + 1, (F.blk - 128) * 8 + F.wave, 128 * 8, 15360, 16384); }
;         }
;         SEAM(p0 + 7); TM_END(8);
.Lmr_331:
	s_or_b64 exec, exec, s[4:5]
	s_nop 0
	v_readlane_b32 s4, v200, 0
	v_readlane_b32 s5, v200, 1
	v_readlane_b32 s6, v200, 2
	v_readlane_b32 s7, v200, 3
	v_readlane_b32 s8, v200, 4
	v_readlane_b32 s9, v200, 5
	v_readlane_b32 s10, v200, 6
	v_readlane_b32 s11, v200, 7
	v_readlane_b32 s12, v200, 8
	v_readlane_b32 s13, v200, 9
	v_readlane_b32 s14, v200, 10
	v_readlane_b32 s15, v200, 11
	v_readlane_b32 s16, v200, 12
	v_readlane_b32 s17, v200, 13
	v_readlane_b32 s18, v200, 14
	v_readlane_b32 s19, v200, 15
	v_readlane_b32 s20, v200, 16
	v_readlane_b32 s21, v200, 17
	v_readlane_b32 s22, v200, 18
	v_readlane_b32 s23, v200, 19
	s_nop 3
.Lmr_skip:
	v_readlane_b32 s4, v255, 44
	s_add_i32 s4, s4, 11
	s_cmp_lt_i32 s4, s97
	s_cselect_b64 s[6:7], -1, 0
	s_and_b64 s[8:9], s[12:13], s[6:7]
	s_andn2_b64 vcc, exec, s[8:9]
	s_cbranch_vccnz .LBB0_1709
	s_waitcnt vmcnt(0)
	s_waitcnt vmcnt(0)
	s_barrier
	s_and_saveexec_b64 s[8:9], s[88:89]
	s_cbranch_execz .LBB0_1708
	v_readlane_b32 s5, v255, 28
	s_waitcnt vmcnt(0) expcnt(0) lgkmcnt(0)
	s_nop 0
	v_mov_b32_e32 v1, s5
	ds_read_b32 v3, v1
	v_readlane_b32 s5, v255, 29
	s_waitcnt lgkmcnt(0)
	v_cmp_ne_u32_e32 vcc, 0, v3
	v_mov_b32_e32 v1, s5
	ds_read_b32 v2, v1
	s_cbranch_vccnz .LBB0_1672
	v_readlane_b32 s12, v253, 0
	v_readlane_b32 s13, v253, 1
	s_load_dwordx2 s[10:11], s[12:13], 0x4
	s_mov_b32 s22, 1
	s_waitcnt lgkmcnt(0)
	s_mul_i32 s5, s10, s3
	s_mul_i32 s5, s5, s11
	s_branch .LBB0_1660
